# w_in GEMM static schedule: the 32 slow rope (k_rope column) tiles of round 2 swapped onto the workgroups that only have four tiles
# speedup vs baseline: 1.0087x; 1.0087x over previous
;     DI bool next(int i_, Unit& u) const {
;         const int i = (npass == 1) ? i_ : i_ / npass, b = i_ - i * npass;
;         const long L = (long)i * G + c; if (L >= nwg) return false;
;         int wgid = (int)L; { const int q = nwg / NXCD, r = nwg % NXCD, xcd = wgid % NXCD, off = wgid / NXCD; wgid = (xcd < r ? xcd * (q + 1) : r * (q + 1) + (xcd - r) * q) + off; }
;         const int nig = WGM * nN, gid = wgid / nig, fm = gid * WGM, gsz = (nM - fm) < WGM ? (nM - fm) : WGM;
;         u.pm = fm + ((wgid % nig) % gsz) + b * pms; u.pn = (wgid % nig) / gsz + b * pns; return true;
.LBB0_430:
	v_readlane_b32 s8, v255, 1
	s_add_i32 s63, s63, 1
	v_readlane_b32 s9, v255, 2
	s_mul_i32 s4, s63, s9
	s_mul_hi_u32 s5, s63, s8
	s_add_i32 s5, s5, s4
	s_mul_i32 s4, s63, s8
	s_mov_b32 s98, s76
	s_cmp_lg_u32 s63, 2
	s_cbranch_scc1 .Lswp_done
	s_cmp_lg_u32 s8, 0x100
	s_cbranch_scc1 .Lswp_done
	s_cmp_ge_u32 s76, 0xe0
	s_cbranch_scc1 .Lswp_hi
	s_cmp_ge_u32 s76, 64
	s_cbranch_scc1 .Lswp_done
	s_bitcmp1_b32 s76, 0
	s_cbranch_scc1 .Lswp_done
	s_lshr_b32 s98, s76, 1
	s_addk_i32 s98, 0xe0
	s_branch .Lswp_done
.Lswp_hi:
	s_sub_i32 s98, s76, 0xe0
	s_lshl_b32 s98, s98, 1
.Lswp_done:
	s_add_u32 s12, s4, s98
	s_addc_u32 s13, s5, s77
	v_mov_b64_e32 v[2:3], 0x4e0
	v_cmp_lt_i64_e64 s[8:9], s[12:13], v[2:3]
	v_mov_b64_e32 v[2:3], 0x4df
	v_cmp_gt_i64_e32 vcc, s[12:13], v[2:3]
	s_cbranch_vccnz .LBB0_432
	s_ashr_i32 s4, s12, 31
	s_lshr_b32 s4, s4, 29
	s_add_i32 s4, s12, s4
	s_ashr_i32 s5, s4, 3
	s_and_b32 s4, s4, -8
	s_sub_i32 s4, s12, s4
	s_cmp_lt_i32 s4, 0
	s_movk_i32 s12, 0x9d
	s_cselect_b32 s12, s12, 0x9c
	s_mul_i32 s4, s4, s12
	s_add_i32 s4, s4, s5
	s_mul_hi_i32 s5, s4, 0xd20d20d3
	s_add_i32 s5, s5, s4
	s_lshr_b32 s12, s5, 31
	s_ashr_i32 s5, s5, 8
	s_add_i32 s5, s5, s12
	s_lshl_b32 s12, s5, 3
	s_sub_i32 s13, 32, s12
	s_min_i32 s13, s13, 8
	s_abs_i32 s14, s13
	v_cvt_f32_u32_e32 v2, s14
	s_sub_i32 s16, 0, s14
	s_mulk_i32 s5, 0x138
	s_sub_i32 s4, s4, s5
	v_rcp_iflag_f32_e32 v2, v2
	s_abs_i32 s5, s4
	s_xor_b32 s15, s4, s13
	s_ashr_i32 s15, s15, 31
	v_mul_f32_e32 v2, 0x4f7ffffe, v2
	v_cvt_u32_f32_e32 v2, v2
	s_nop 0
	v_readfirstlane_b32 s17, v2
	s_mul_i32 s16, s16, s17
	s_mul_hi_u32 s16, s17, s16
	s_add_i32 s17, s17, s16
	s_mul_hi_u32 s16, s5, s17
	s_mul_i32 s17, s16, s14
	s_sub_i32 s5, s5, s17
	s_add_i32 s33, s16, 1
	s_sub_i32 s17, s5, s14
	s_cmp_ge_u32 s5, s14
	s_cselect_b32 s16, s33, s16
	s_cselect_b32 s5, s17, s5
	s_add_i32 s17, s16, 1
	s_cmp_ge_u32 s5, s14
	s_cselect_b32 s5, s17, s16
	s_xor_b32 s5, s5, s15
	s_sub_i32 s40, s5, s15
	s_mul_i32 s5, s40, s13
	s_sub_i32 s4, s4, s5
	s_add_i32 s42, s12, s4
